# ffn_up: acc->LDS dump and conv weight loads issued right after the K-loop (before next-tile scheduling/prefetch), counted vmcnt wait; GEMM tile tops zero-init after stage ds_writes; resid K-loop trail
# baseline (speedup 1.0000x reference)
; #define LWRITE(RA, RB, BUF) do { char* w_ = wa + (BUF) * STAGE; _Pragma("unroll") for (int j = 0; j < NA; ++j) *(u32x4*)(w_ + j * 64 * PITCH) = RA[j]; _Pragma("unroll") for (int j = 0; j < NB; ++j) *(u32x4*)(w_ + AB + j * 64 * PITCH) = RB[j]; } while (0)
; #define LWRITE(RA, RB, BUF) do { char* w_ = wa + (BUF) * STAGE; _Pragma("unroll") for (int j = 0; j < NA; ++j) *(u32x4*)(w_ + j * 64 * RB_) = RA[j]; _Pragma("unroll") for (int j = 0; j < NB; ++j) *(u32x4*)(w_ + AB + j * 64 * RB_) = RB[j]; } while (0)
; template <bool SW, class AL, class BL>
; DI void gemm_run16(int tid, char* lds, const AL& al, const BL& bl, int nk, f32x4 (&acc)[4][4], u32x4 (&ra0)[4], u32x4 (&rb0)[2], u32x4 (&ra1)[4], u32x4 (&rb1)[2]) {
;     ...
;   const int kl = nk - 1;
;   LWRITE(ra0, rb0, 0);
;   __syncthreads();
; static __device__ __forceinline__ void phase_inproj(const P& p, int l, char* lds) {
;     ...
;     f32x4 acc[4][4];
; #pragma unroll
;     for (int a_ = 0; a_ < 4; ++a_)
; #pragma unroll
;       for (int b_ = 0; b_ < 4; ++b_) acc[a_][b_] = f32x4{0.f, 0.f, 0.f, 0.f};
;     __syncthreads();
;     gemm_run16<false>(tid, lds + LDS_SCR, al, bl, 16, acc, ra0, rb0, ra1, rb1);
.LBB0_288:
	s_mov_b32 s18, s22
	s_mov_b32 s19, s23
	s_mov_b32 s0, -2
	s_waitcnt vmcnt(4)
	s_barrier
	ds_write_b128 v203, v[26:29] offset:2304
	ds_write_b128 v203, v[30:33] offset:10496
	ds_write_b128 v203, v[34:37] offset:18688
	ds_write_b128 v203, v[42:45] offset:26880
	s_waitcnt vmcnt(3)
	ds_write_b128 v203, v[38:41] offset:35072
	s_waitcnt vmcnt(1)
	ds_write_b128 v203, v[46:49] offset:43264
	s_waitcnt vmcnt(0)
	ds_write_b128 v203, v[14:17] offset:51456
	ds_write_b128 v203, v[18:21] offset:59648
	ds_write_b128 v209, v[22:25]
	ds_write_b128 v210, v[6:9]
	ds_write_b128 v211, v[2:5]
	ds_write_b128 v212, v[10:13]
	v_mov_b64_e32 v[50:51], 0
	v_mov_b64_e32 v[52:53], 0
	v_mov_b64_e32 v[54:55], 0
	v_mov_b64_e32 v[56:57], 0
	v_mov_b64_e32 v[58:59], 0
	v_mov_b64_e32 v[60:61], 0
	v_mov_b64_e32 v[62:63], 0
	v_mov_b64_e32 v[64:65], 0
	v_mov_b64_e32 v[66:67], 0
	v_mov_b64_e32 v[68:69], 0
	v_mov_b64_e32 v[70:71], 0
	v_mov_b64_e32 v[72:73], 0
	v_mov_b64_e32 v[74:75], 0
	v_mov_b64_e32 v[76:77], 0
	v_mov_b64_e32 v[78:79], 0
	v_mov_b64_e32 v[80:81], 0
	v_mov_b64_e32 v[82:83], 0
	v_mov_b64_e32 v[84:85], 0
	v_mov_b64_e32 v[86:87], 0
	v_mov_b64_e32 v[88:89], 0
	v_mov_b64_e32 v[90:91], 0
	v_mov_b64_e32 v[92:93], 0
	v_mov_b64_e32 v[94:95], 0
	v_mov_b64_e32 v[96:97], 0
	v_mov_b64_e32 v[98:99], 0
	v_mov_b64_e32 v[100:101], 0
	v_mov_b64_e32 v[102:103], 0
	v_mov_b64_e32 v[104:105], 0
	v_mov_b64_e32 v[106:107], 0
	v_mov_b64_e32 v[108:109], 0
	v_mov_b64_e32 v[110:111], 0
	v_mov_b64_e32 v[112:113], 0
	s_waitcnt lgkmcnt(0)
	s_barrier

; #define GLOAD(RA, RB, KT) do { const int kc_ = (KT) * 8 + lc; _Pragma("unroll") for (int j = 0; j < NA; ++j) RA[j] = al.load(j, kc_); _Pragma("unroll") for (int j = 0; j < NB; ++j) RB[j] = bl.load(j, kc_); } while (0)
; #define LWRITE(RA, RB, BUF) do { char* w_ = wa + (BUF) * STAGE; _Pragma("unroll") for (int j = 0; j < NA; ++j) *(u32x4*)(w_ + j * 64 * PITCH) = RA[j]; _Pragma("unroll") for (int j = 0; j < NB; ++j) *(u32x4*)(w_ + AB + j * 64 * PITCH) = RB[j]; } while (0)
; #define GLOAD(RA, RB, KT) do { const int kc_ = (KT) * 8 + lc; _Pragma("unroll") for (int j = 0; j < NA; ++j) RA[j] = al.load(j, kc_); _Pragma("unroll") for (int j = 0; j < NB; ++j) RB[j] = bl.load(j, kc_); } while (0)
; #define LWRITE(RA, RB, BUF) do { char* w_ = wa + (BUF) * STAGE; _Pragma("unroll") for (int j = 0; j < NA; ++j) *(u32x4*)(w_ + j * 64 * RB_) = RA[j]; _Pragma("unroll") for (int j = 0; j < NB; ++j) *(u32x4*)(w_ + AB + j * 64 * RB_) = RB[j]; } while (0)
; #define COMPUTE(BUF, RA, RB, WBUF) do { const char* sb = lds + (BUF) * STAGE; char* w_ = wa + (WBUF) * STAGE; \
;     KSTEP(o0); *(u32x4*)(w_) = RA[0]; *(u32x4*)(w_ + 64 * RB_) = RA[1]; *(u32x4*)(w_ + 128 * RB_) = RA[2]; \
;     KSTEP(o1); *(u32x4*)(w_ + 192 * RB_) = RA[3]; *(u32x4*)(w_ + AB) = RB[0]; *(u32x4*)(w_ + AB + 64 * RB_) = RB[1]; } while (0)
; template <int WM, int WN, int TM, int TN, bool SW = false, class AL, class BL>
; DI void gemm_run(int tid, char* lds, const AL& al, const BL& bl, int nk, f32x16 (&acc)[TM][TN], u32x4 (&ra0)[WM * TM / 2], u32x4 (&rb0)[WN * TN / 2], u32x4 (&ra1)[WM * TM / 2], u32x4 (&rb1)[WN * TN / 2]) {
;     ...
;   const int kl = nk - 1;
;   LWRITE(ra0, rb0, 0);
;   __syncthreads();
; #pragma unroll 1
;   for (int kt = 0; kt < nk; kt += 2) {
;     GLOAD(ra0, rb0, (kt + 2 < kl ? kt + 2 : kl));
;     COMPUTE(0, ra1, rb1, 1);
;     __syncthreads();
;     if (kt + 1 >= nk) break;
;     GLOAD(ra1, rb1, (kt + 3 < kl ? kt + 3 : kl));
;     COMPUTE(1, ra0, rb0, 0);
;     __syncthreads();
;   }
.LBB0_912:
	ds_read_b128 v[90:93], v213 offset:2304
	v_add_u32_e32 v136, 0, v128
	ds_read_b128 v[94:97], v213 offset:2336
	ds_read_b128 v[98:101], v136 offset:39168
	ds_read_b128 v[102:105], v136 offset:39200
	ds_read_b128 v[106:109], v136 offset:43776
	ds_read_b128 v[110:113], v136 offset:43808
	v_add_u32_e32 v0, 0x14d00, v212
	s_add_i32 s7, s6, 4
	s_min_u32 s7, s7, 15
	s_waitcnt lgkmcnt(3)
	v_mfma_f32_32x32x16_bf16 v[50:65], v[90:93], v[98:101], v[50:65]
	s_waitcnt lgkmcnt(1)
	v_mfma_f32_32x32x16_bf16 v[18:33], v[90:93], v[106:109], v[18:33]
	ds_read_b128 v[90:93], v213 offset:6912
	ds_read_b128 v[132:135], v213 offset:6944
	s_waitcnt vmcnt(5)
	ds_write_b128 v212, v[82:85] offset:57600
	s_waitcnt vmcnt(2)
	ds_write_b128 v0, v[86:89]
	ds_read_b128 v[82:85], v213 offset:2368
	ds_read_b128 v[86:89], v136 offset:39232
	v_add_u32_e32 v0, 0x900, v212
	v_mfma_f32_32x32x16_bf16 v[50:65], v[94:97], v[102:105], v[50:65]
	s_waitcnt lgkmcnt(6)
	v_mfma_f32_32x32x16_bf16 v[18:33], v[94:97], v[110:113], v[18:33]
	s_waitcnt lgkmcnt(5)
	v_mfma_f32_32x32x16_bf16 v[34:49], v[90:93], v[98:101], v[34:49]
	v_mfma_f32_32x32x16_bf16 v[2:17], v[90:93], v[106:109], v[2:17]
	ds_read_b128 v[90:93], v136 offset:43840
	s_waitcnt lgkmcnt(1)
	v_mfma_f32_32x32x16_bf16 v[50:65], v[82:85], v[86:89], v[50:65]
	s_waitcnt lgkmcnt(0)
	v_mfma_f32_32x32x16_bf16 v[18:33], v[82:85], v[90:93], v[18:33]
	ds_read_b128 v[82:85], v213 offset:6976
	ds_write_b128 v0, v[70:73] offset:64512
	v_add_u32_e32 v0, 0x17100, v212
	s_waitcnt vmcnt(1)
	ds_write_b128 v0, v[78:81]
	ds_read_b128 v[70:73], v213 offset:2400
	ds_read_b128 v[78:81], v136 offset:39264
	v_lshl_or_b32 v0, s7, 7, v120
	v_lshl_add_u64 v[94:95], v[116:117], 0, v[0:1]
	v_mfma_f32_32x32x16_bf16 v[34:49], v[132:135], v[102:105], v[34:49]
	v_lshl_add_u64 v[98:99], v[118:119], 0, v[0:1]
	v_lshl_add_u64 v[96:97], v[122:123], 0, v[0:1]
	s_add_i32 s7, s6, 2
	s_min_u32 s6, s7, 12
	s_cmp_lt_u32 s7, 14
	v_mfma_f32_32x32x16_bf16 v[2:17], v[132:135], v[110:113], v[2:17]
	s_waitcnt lgkmcnt(4)
	v_mfma_f32_32x32x16_bf16 v[34:49], v[82:85], v[86:89], v[34:49]
	v_mfma_f32_32x32x16_bf16 v[2:17], v[82:85], v[90:93], v[2:17]
	ds_read_b128 v[82:85], v213 offset:7008
	ds_read_b128 v[86:89], v136 offset:43872
	v_lshl_add_u64 v[90:91], v[114:115], 0, v[0:1]
	s_waitcnt lgkmcnt(2)
	v_mfma_f32_32x32x16_bf16 v[50:65], v[70:73], v[78:81], v[50:65]
	s_waitcnt lgkmcnt(0)
	v_mfma_f32_32x32x16_bf16 v[18:33], v[70:73], v[86:89], v[18:33]
	v_lshl_add_u64 v[70:71], v[124:125], 0, v[0:1]
	v_lshl_add_u64 v[72:73], v[126:127], 0, v[0:1]
	v_add_u32_e32 v0, 0x12900, v212
	ds_write_b128 v0, v[66:69]
	s_waitcnt vmcnt(0)
	ds_write_b128 v129, v[74:77]
	global_load_dwordx4 v[90:93], v[90:91], off
	s_nop 0
	global_load_dwordx4 v[102:105], v[96:97], off
	s_nop 0
	global_load_dwordx4 v[94:97], v[94:95], off
	s_nop 0
	global_load_dwordx4 v[98:101], v[98:99], off
	s_nop 0
	global_load_dwordx4 v[106:109], v[70:71], off
	global_load_dwordx4 v[110:113], v[72:73], off
	s_waitcnt lgkmcnt(0)
	v_mfma_f32_32x32x16_bf16 v[34:49], v[82:85], v[78:81], v[34:49]
	s_barrier
	ds_read_b128 v[66:69], v213 offset:57600
	ds_read_b128 v[70:73], v214 offset:57600
	ds_read_b128 v[74:77], v213 offset:57632
	ds_read_b128 v[78:81], v214 offset:57632
	v_lshl_or_b32 v0, s6, 7, v120
	v_lshl_add_u64 v[136:137], v[116:117], 0, v[0:1]
	v_lshl_add_u64 v[138:139], v[124:125], 0, v[0:1]
	v_lshl_add_u64 v[144:145], v[126:127], 0, v[0:1]
	v_mfma_f32_32x32x16_bf16 v[2:17], v[82:85], v[86:89], v[2:17]
	ds_read_b128 v[82:85], v214 offset:62208
	ds_read_b128 v[86:89], v214 offset:62240
	s_mov_b32 s6, s7
	s_waitcnt lgkmcnt(4)
	v_mfma_f32_32x32x16_bf16 v[50:65], v[66:69], v[70:73], v[50:65]
	s_waitcnt lgkmcnt(1)
	v_mfma_f32_32x32x16_bf16 v[18:33], v[66:69], v[82:85], v[18:33]
	ds_read_b128 v[66:69], v213 offset:62208
	ds_read_b128 v[132:135], v213 offset:62240
	s_waitcnt vmcnt(5)
	ds_write_b128 v212, v[90:93] offset:2304
	s_waitcnt vmcnt(4)
	ds_write_b128 v212, v[102:105] offset:29952
	s_waitcnt lgkmcnt(3)
	v_mfma_f32_32x32x16_bf16 v[34:49], v[66:69], v[70:73], v[34:49]
	v_mfma_f32_32x32x16_bf16 v[2:17], v[66:69], v[82:85], v[2:17]
	ds_read_b128 v[66:69], v213 offset:57664
	ds_read_b128 v[70:73], v214 offset:57664
	v_lshl_add_u64 v[82:83], v[114:115], 0, v[0:1]
	v_mfma_f32_32x32x16_bf16 v[50:65], v[74:77], v[78:81], v[50:65]
	v_mfma_f32_32x32x16_bf16 v[18:33], v[74:77], v[86:89], v[18:33]
	ds_read_b128 v[74:77], v214 offset:62272
	s_waitcnt lgkmcnt(5)
	v_mfma_f32_32x32x16_bf16 v[34:49], v[132:135], v[78:81], v[34:49]
	ds_read_b128 v[78:81], v213 offset:62272
	v_mfma_f32_32x32x16_bf16 v[2:17], v[132:135], v[86:89], v[2:17]
	v_lshl_add_u64 v[86:87], v[118:119], 0, v[0:1]
	v_lshl_add_u64 v[88:89], v[122:123], 0, v[0:1]
	s_waitcnt lgkmcnt(2)
	v_mfma_f32_32x32x16_bf16 v[50:65], v[66:69], v[70:73], v[50:65]
	s_waitcnt lgkmcnt(1)
	v_mfma_f32_32x32x16_bf16 v[18:33], v[66:69], v[74:77], v[18:33]
	s_waitcnt lgkmcnt(0)
	v_mfma_f32_32x32x16_bf16 v[34:49], v[78:81], v[70:73], v[34:49]
	global_load_dwordx4 v[82:85], v[82:83], off offset:384
	s_nop 0
	global_load_dwordx4 v[70:73], v[136:137], off offset:384
	global_load_dwordx4 v[66:69], v[86:87], off offset:384
	s_waitcnt vmcnt(6)
	ds_write_b128 v212, v[94:97] offset:11520
	s_waitcnt vmcnt(4)
	ds_write_b128 v212, v[106:109] offset:39168
	v_mfma_f32_32x32x16_bf16 v[2:17], v[78:81], v[74:77], v[2:17]
	ds_read_b128 v[74:77], v213 offset:57696
	ds_read_b128 v[132:135], v214 offset:57696
	global_load_dwordx4 v[86:89], v[88:89], off offset:384
	s_nop 0
	global_load_dwordx4 v[78:81], v[138:139], off offset:384
	ds_read_b128 v[136:139], v214 offset:62304
	ds_read_b128 v[140:143], v213 offset:62304
	s_waitcnt lgkmcnt(2)
	v_mfma_f32_32x32x16_bf16 v[50:65], v[74:77], v[132:135], v[50:65]
	s_waitcnt lgkmcnt(1)
	v_mfma_f32_32x32x16_bf16 v[18:33], v[74:77], v[136:139], v[18:33]
	global_load_dwordx4 v[74:77], v[144:145], off offset:384
	ds_write_b128 v212, v[98:101] offset:20736
	s_waitcnt vmcnt(6)
	ds_write_b128 v212, v[110:113] offset:48384
	s_waitcnt lgkmcnt(2)
	v_mfma_f32_32x32x16_bf16 v[34:49], v[140:143], v[132:135], v[34:49]
	v_mfma_f32_32x32x16_bf16 v[2:17], v[140:143], v[136:139], v[2:17]
	s_waitcnt lgkmcnt(0)
	s_barrier
	s_cbranch_scc1 .LBB0_912
	s_add_i32 s8, s5, 1
	s_cmp_ge_i32 s8, s4
	s_cbranch_scc1 .LBB0_926
	s_lshl_b32 s6, s5, 5
	v_readlane_b32 s7, v254, 27
	s_add_i32 s21, s7, s6
	s_lshl_b32 s5, s5, 3
	v_readlane_b32 s6, v254, 25
	s_add_i32 s23, s6, s5
	s_mul_i32 s5, s66, s8
	s_add_i32 s9, s94, s5
	s_mov_b32 s24, 0
	s_mov_b32 s25, 0
	s_branch .LBB0_916

; #define LWRITE(RA, RB, BUF) do { char* w_ = wa + (BUF) * STAGE; _Pragma("unroll") for (int j = 0; j < NA; ++j) *(u32x4*)(w_ + j * 64 * PITCH) = RA[j]; _Pragma("unroll") for (int j = 0; j < NB; ++j) *(u32x4*)(w_ + AB + j * 64 * PITCH) = RB[j]; } while (0)
; #define LWRITE(RA, RB, BUF) do { char* w_ = wa + (BUF) * STAGE; _Pragma("unroll") for (int j = 0; j < NA; ++j) *(u32x4*)(w_ + j * 64 * RB_) = RA[j]; _Pragma("unroll") for (int j = 0; j < NB; ++j) *(u32x4*)(w_ + AB + j * 64 * RB_) = RB[j]; } while (0)
; template <bool SW, class AL, class BL>
; DI void gemm_run16(int tid, char* lds, const AL& al, const BL& bl, int nk, f32x4 (&acc)[4][4], u32x4 (&ra0)[4], u32x4 (&rb0)[2], u32x4 (&ra1)[4], u32x4 (&rb1)[2]) {
;     ...
;   const int kl = nk - 1;
;   LWRITE(ra0, rb0, 0);
;   __syncthreads();
; static __device__ __forceinline__ void phase_ffn_up(const P& p, int l, char* lds) {
;     ...
;     f32x4 acc[4][4];
; #pragma unroll
;     for (int a_ = 0; a_ < 4; ++a_)
; #pragma unroll
;       for (int b_ = 0; b_ < 4; ++b_) acc[a_][b_] = f32x4{0.f, 0.f, 0.f, 0.f};
;     __syncthreads();
;     gemm_run16<false>(tid, lds + LDS_SCR, al, bl, 16, acc, ra0, rb0, ra1, rb1);
.LBB0_1059:
	s_mov_b32 s34, s31
	s_mov_b32 s35, s33
	s_mov_b32 s18, -2
	s_barrier
	s_waitcnt vmcnt(11)
	ds_write_b128 v141, v[26:29] offset:2304
	s_waitcnt vmcnt(9)
	ds_write_b128 v141, v[30:33] offset:10496
	s_waitcnt vmcnt(7)
	ds_write_b128 v141, v[34:37] offset:18688
	s_waitcnt vmcnt(5)
	ds_write_b128 v141, v[38:41] offset:26880
	s_waitcnt vmcnt(3)
	ds_write_b128 v141, v[42:45] offset:35072
	s_waitcnt vmcnt(1)
	ds_write_b128 v141, v[46:49] offset:43264
	s_waitcnt vmcnt(0)
	ds_write_b128 v141, v[14:17] offset:51456
	ds_write_b128 v141, v[18:21] offset:59648
	ds_write_b128 v146, v[22:25]
	ds_write_b128 v147, v[2:5]
	ds_write_b128 v148, v[6:9]
	ds_write_b128 v149, v[10:13]
	v_mov_b64_e32 v[50:51], 0
	v_mov_b64_e32 v[52:53], 0
	v_mov_b64_e32 v[54:55], 0
	v_mov_b64_e32 v[56:57], 0
	v_mov_b64_e32 v[58:59], 0
	v_mov_b64_e32 v[60:61], 0
	v_mov_b64_e32 v[62:63], 0
	v_mov_b64_e32 v[64:65], 0
	v_mov_b64_e32 v[66:67], 0
	v_mov_b64_e32 v[68:69], 0
	v_mov_b64_e32 v[70:71], 0
	v_mov_b64_e32 v[72:73], 0
	v_mov_b64_e32 v[74:75], 0
	v_mov_b64_e32 v[76:77], 0
	v_mov_b64_e32 v[78:79], 0
	v_mov_b64_e32 v[80:81], 0
	v_mov_b64_e32 v[82:83], 0
	v_mov_b64_e32 v[84:85], 0
	v_mov_b64_e32 v[86:87], 0
	v_mov_b64_e32 v[88:89], 0
	v_mov_b64_e32 v[90:91], 0
	v_mov_b64_e32 v[92:93], 0
	v_mov_b64_e32 v[94:95], 0
	v_mov_b64_e32 v[96:97], 0
	v_mov_b64_e32 v[98:99], 0
	v_mov_b64_e32 v[100:101], 0
	v_mov_b64_e32 v[102:103], 0
	v_mov_b64_e32 v[104:105], 0
	v_mov_b64_e32 v[106:107], 0
	v_mov_b64_e32 v[108:109], 0
	v_mov_b64_e32 v[110:111], 0
	v_mov_b64_e32 v[112:113], 0
	s_waitcnt lgkmcnt(0)
	s_barrier

; static __device__ __forceinline__ void phase_ffn_up(const P& p, int l, char* lds) {
;     ...
; #pragma unroll
;     for (int tm = 0; tm < 4; ++tm) {
;       char* trow = tile + (wm * 64 + 16 * tm + (lane & 15)) * 528 + (wn * 64 + 4 * (lane >> 4)) * 4;
; #pragma unroll
;       for (int tn = 0; tn < 4; ++tn) *(f32x4*)(trow + 64 * tn) = acc[tm][tn];
;     }
;     __syncthreads();
;     {
;       const int cgp = tid & 7, wn2 = cgp >> 2, j0 = (cgp & 3) * 8;
;       const int ca0 = nt * 64 + wn2 * 32 + j0;
;       const int lca = (wn2 * 64 + j0) * 4, lcg = lca + 128;
;       float wa0[8], wa1[8], wa2[8], ba[8], wg0[8], wg1[8], wg2[8], bg[8];
; #pragma unroll
;       for (int e = 0; e < 8; ++e) {
;         wa0[e] = cw[ca0 + e]; wa1[e] = cw[5632 + ca0 + e]; wa2[e] = cw[2 * 5632 + ca0 + e]; ba[e] = cb[ca0 + e];
;         wg0[e] = cw[DFF + ca0 + e]; wg1[e] = cw[5632 + DFF + ca0 + e]; wg2[e] = cw[2 * 5632 + DFF + ca0 + e]; bg[e] = cb[DFF + ca0 + e];
;       }
.Lffn_skip2:
	v_mfma_f32_16x16x32_bf16 v[106:109], v[170:173], v[110:113], v[162:165]
	v_mfma_f32_16x16x32_bf16 v[110:113], v[174:177], v[110:113], v[166:169]
	s_cmp_lt_u32 s19, 14
	s_cbranch_scc1 .LBB0_1060
	s_nop 7
	s_nop 7
	s_nop 3
	v_lshl_or_b32 v114, s35, 6, v152
	v_ashrrev_i32_e32 v115, 31, v114
	ds_write_b128 v155, v[50:53] offset:2304
	ds_write_b128 v155, v[54:57] offset:2368
	ds_write_b128 v155, v[58:61] offset:2432
	ds_write_b128 v155, v[62:65] offset:2496
	ds_write_b128 v155, v[66:69] offset:10752
	ds_write_b128 v155, v[70:73] offset:10816
	ds_write_b128 v155, v[74:77] offset:10880
	ds_write_b128 v155, v[78:81] offset:10944
	ds_write_b128 v155, v[82:85] offset:19200
	ds_write_b128 v155, v[86:89] offset:19264
	ds_write_b128 v155, v[90:93] offset:19328
	ds_write_b128 v155, v[94:97] offset:19392
	ds_write_b128 v155, v[102:105] offset:27648
	ds_write_b128 v155, v[98:101] offset:27712
	ds_write_b128 v155, v[106:109] offset:27776
	ds_write_b128 v155, v[110:113] offset:27840
	v_lshlrev_b64 v[50:51], 2, v[114:115]
	v_lshl_add_u64 v[74:75], s[12:13], 0, v[50:51]
	s_mov_b64 s[20:21], 0x5800
	v_lshl_add_u64 v[54:55], v[74:75], 0, s[20:21]
	s_mov_b64 s[20:21], 0xb000
	v_lshl_add_u64 v[56:57], v[74:75], 0, s[20:21]
	s_mov_b64 s[20:21], 0x8400
	v_lshl_add_u64 v[70:71], v[74:75], 0, s[20:21]
	s_mov_b64 s[20:21], 0xdc00
	v_lshl_add_u64 v[76:77], v[74:75], 0, s[20:21]
	s_movk_i32 s20, 0x5000
	v_lshl_add_u64 v[78:79], s[16:17], 0, v[50:51]
	s_mov_b64 s[14:15], 0x2c00
	v_add_co_u32_e32 v58, vcc, s20, v74
	v_lshl_add_u64 v[66:67], v[74:75], 0, s[14:15]
	v_lshl_add_u64 v[80:81], v[78:79], 0, s[14:15]
	v_addc_co_u32_e32 v59, vcc, 0, v75, vcc
	s_mov_b32 s14, 0xb000
	v_add_co_u32_e32 v60, vcc, s14, v74
	s_movk_i32 s15, 0x2000
	s_nop 0
	v_addc_co_u32_e32 v61, vcc, 0, v75, vcc
	v_add_co_u32_e32 v68, vcc, s15, v74
	s_mov_b32 s14, 0x8000
	s_nop 0
	v_addc_co_u32_e32 v69, vcc, 0, v75, vcc
	v_add_co_u32_e32 v72, vcc, s14, v74
	s_mov_b32 s20, 0xd000
	s_nop 0
	v_addc_co_u32_e32 v73, vcc, 0, v75, vcc
	s_waitcnt lgkmcnt(0)
	global_load_dwordx4 v[50:53], v[74:75], off offset:16
	global_load_dwordx4 v[86:89], v[74:75], off
	global_load_dwordx4 v[94:97], v[58:59], off offset:2048
	global_load_dwordx4 v[90:93], v[60:61], off
	s_nop 0
	global_load_dwordx4 v[58:61], v[54:55], off offset:16
	s_nop 0
	global_load_dwordx4 v[54:57], v[56:57], off offset:16
	s_nop 0
	global_load_dwordx4 v[62:65], v[78:79], off offset:16
	global_load_dwordx4 v[82:85], v[78:79], off
	v_add_co_u32_e32 v74, vcc, s20, v74
	global_load_dwordx4 v[98:101], v[68:69], off offset:3072
	global_load_dwordx4 v[102:105], v[72:73], off offset:1024
	s_nop 0
	global_load_dwordx4 v[66:69], v[66:67], off offset:16
	s_nop 0
	global_load_dwordx4 v[70:73], v[70:71], off offset:16
	v_addc_co_u32_e32 v75, vcc, 0, v75, vcc
	v_add_co_u32_e32 v78, vcc, s15, v78
	global_load_dwordx4 v[106:109], v[74:75], off offset:3072
	s_nop 0
	global_load_dwordx4 v[74:77], v[76:77], off offset:16
	v_addc_co_u32_e32 v79, vcc, 0, v79, vcc
	global_load_dwordx4 v[110:113], v[78:79], off offset:3072
	s_nop 0
	global_load_dwordx4 v[78:81], v[80:81], off offset:16
	s_add_i32 s20, s29, 1
	s_cmp_ge_i32 s20, s28
	s_cbranch_scc1 .LBB0_1072
	s_lshl_b32 s18, s29, 3
	v_readlane_b32 s14, v254, 25
	s_add_i32 s37, s14, s18
	s_mul_i32 s18, s66, s20
	s_add_i32 s21, s94, s18
	s_mov_b32 s31, 0
	s_mov_b32 s33, 0
	s_branch .LBB0_1064

; static __device__ __forceinline__ void phase_ffn_up(const P& p, int l, char* lds) {
;     ...
;   auto mk = [&](int rt_, int nt_, LdRows& a_, LdRows& b_) {
;     const int ts_ = 254 * rt_ - 1;
; #pragma unroll
;     for (int j = 0; j < 4; ++j) { const int tt = ts_ + lr + 64 * j; a_.p[j] = (tt >= 0 && tt < MTOT) ? H + (size_t)tt * 1024 : (const u16*)(p.ws + OFF_ZERO); }
; #pragma unroll
;     for (int j = 0; j < 2; ++j) b_.p[j] = W + (size_t)(nt_ * 128 + lr + 64 * j) * 1024;
;     b_.p[2] = b_.p[3] = b_.p[0];
;   };
;   int s = tile_next(0, ns, RT, 44, 8, 4, rt, nt);
;   if (s >= 0) { mk(rt, nt, al, bl); gemm_issue<4, 2>(tid, al, bl, 16, ra0, rb0, ra1, rb1); }
;   while (s >= 0) {
;     const int tstart = 254 * rt - 1;
;     f32x4 acc[4][4];
; #pragma unroll
;     for (int a_ = 0; a_ < 4; ++a_)
; #pragma unroll
;       for (int b_ = 0; b_ < 4; ++b_) acc[a_][b_] = f32x4{0.f, 0.f, 0.f, 0.f};
;     __syncthreads();
;     gemm_run16<false>(tid, lds + LDS_SCR, al, bl, 16, acc, ra0, rb0, ra1, rb1);
;     int rt2 = 0, nt2 = 0; const int s2 = tile_next(s + 1, ns, RT, 44, 8, 4, rt2, nt2);
;     if (s2 >= 0) { mk(rt2, nt2, al, bl); gemm_issue<4, 2>(tid, al, bl, 16, ra0, rb0, ra1, rb1); }
; #pragma unroll
;     for (int tm = 0; tm < 4; ++tm) {
;       char* trow = tile + (wm * 64 + 16 * tm + (lane & 15)) * 528 + (wn * 64 + 4 * (lane >> 4)) * 4;
; #pragma unroll
;       for (int tn = 0; tn < 4; ++tn) *(f32x4*)(trow + 64 * tn) = acc[tm][tn];
;     }
;     __syncthreads();
;     {
;       const int cgp = tid & 7, wn2 = cgp >> 2, j0 = (cgp & 3) * 8;
;       const int ca0 = nt * 64 + wn2 * 32 + j0;
;       const int lca = (wn2 * 64 + j0) * 4, lcg = lca + 128;
;       float wa0[8], wa1[8], wa2[8], ba[8], wg0[8], wg1[8], wg2[8], bg[8];
; #pragma unroll
;       for (int e = 0; e < 8; ++e) {
;         wa0[e] = cw[ca0 + e]; wa1[e] = cw[5632 + ca0 + e]; wa2[e] = cw[2 * 5632 + ca0 + e]; ba[e] = cb[ca0 + e];
;         wg0[e] = cw[DFF + ca0 + e]; wg1[e] = cw[5632 + DFF + ca0 + e]; wg2[e] = cw[2 * 5632 + DFF + ca0 + e]; bg[e] = cb[DFF + ca0 + e];
;       }
.LBB0_1075:
	s_cmp_lt_i32 s29, 0
	s_cselect_b64 s[18:19], -1, 0
	s_and_b64 vcc, exec, s[18:19]
	s_cbranch_vccnz .LBB0_1077
	s_mul_i32 s20, s31, 0xfe
	v_add_u32_e32 v4, s20, v140
	v_readlane_b32 s14, v254, 20
	v_lshlrev_b32_e32 v0, 11, v4
	s_mov_b32 s15, 0x10800
	v_mov_b32_e32 v5, s14
	v_readlane_b32 s14, v254, 19
	v_lshl_add_u64 v[2:3], s[60:61], 0, v[0:1]
	v_cmp_gt_u32_e32 vcc, s15, v4
	v_mov_b32_e32 v6, s14
	v_add_u32_e32 v7, 64, v4
	v_cndmask_b32_e32 v119, v5, v3, vcc
	v_cndmask_b32_e32 v118, v6, v2, vcc
	v_lshlrev_b32_e32 v0, 11, v7
	v_cmp_gt_u32_e32 vcc, s15, v7
	v_add_u32_e32 v7, 0x80, v4
	v_lshl_add_u64 v[2:3], s[60:61], 0, v[0:1]
	v_lshlrev_b32_e32 v0, 11, v7
	v_add_u32_e32 v4, 0xc0, v4
	v_cndmask_b32_e32 v121, v5, v3, vcc
	v_cndmask_b32_e32 v120, v6, v2, vcc
	v_lshl_add_u64 v[2:3], s[60:61], 0, v[0:1]
	v_cmp_gt_u32_e32 vcc, s15, v7
	v_lshlrev_b32_e32 v0, 11, v4
	s_nop 0
	v_cndmask_b32_e32 v125, v5, v3, vcc
	v_cndmask_b32_e32 v124, v6, v2, vcc
	v_lshl_add_u64 v[2:3], s[60:61], 0, v[0:1]
	v_cmp_gt_u32_e32 vcc, s15, v4
	s_nop 1
	v_cndmask_b32_e32 v126, v6, v2, vcc
	v_lshl_add_u32 v2, s33, 7, v135
	v_cndmask_b32_e32 v127, v5, v3, vcc
	v_ashrrev_i32_e32 v3, 31, v2
	v_lshlrev_b64 v[4:5], 11, v[2:3]
	v_add_u32_e32 v2, 64, v2
	v_ashrrev_i32_e32 v3, 31, v2
	v_lshlrev_b64 v[2:3], 11, v[2:3]
	v_lshl_add_u64 v[128:129], s[0:1], 0, v[4:5]
	v_lshl_add_u64 v[130:131], s[0:1], 0, v[2:3]
	v_lshl_add_u64 v[2:3], v[118:119], 0, v[122:123]
	v_lshl_add_u64 v[4:5], v[120:121], 0, v[122:123]
	v_lshl_add_u64 v[6:7], v[124:125], 0, v[122:123]
	v_lshl_add_u64 v[8:9], v[126:127], 0, v[122:123]
	v_lshl_add_u64 v[10:11], v[128:129], 0, v[122:123]
	v_lshl_add_u64 v[12:13], v[130:131], 0, v[122:123]
	global_load_dwordx4 v[26:29], v[2:3], off
	global_load_dwordx4 v[14:17], v[2:3], off offset:128
	global_load_dwordx4 v[30:33], v[4:5], off
	global_load_dwordx4 v[18:21], v[4:5], off offset:128
	global_load_dwordx4 v[34:37], v[6:7], off
	global_load_dwordx4 v[22:25], v[6:7], off offset:128
	global_load_dwordx4 v[38:41], v[8:9], off
	s_nop 0
	global_load_dwordx4 v[2:5], v[8:9], off offset:128
	global_load_dwordx4 v[42:45], v[10:11], off
	s_nop 0
	global_load_dwordx4 v[6:9], v[10:11], off offset:128
	global_load_dwordx4 v[46:49], v[12:13], off
	s_nop 0
	global_load_dwordx4 v[10:13], v[12:13], off offset:128
.LBB0_1077:
	s_barrier
	s_mulk_i32 s34, 0xfe
	v_readlane_b32 s14, v254, 51
	v_add_u32_e32 v158, s34, v140
	v_readlane_b32 s15, v254, 52
	v_cmp_gt_i32_e32 vcc, s24, v158
	s_movk_i32 s81, 0x2000
	v_lshl_add_u64 v[132:133], v[114:115], 1, s[14:15]
	s_and_b64 s[22:23], s[4:5], vcc
	s_cmp_lt_i32 s29, 0
	s_cbranch_scc1 .Lwt_all
	s_waitcnt vmcnt(12)
	s_branch .Lwt_done
.Lwt_all:
	s_waitcnt vmcnt(0)
; DI unsigned pk2(float a, float b) { f32x2 v = {a, b}; bf16x2_t r = __builtin_convertvector(v, bf16x2_t); return __builtin_bit_cast(unsigned, r); }
; DI float silu_f(float g) { return g * rcpf_(1.f + ex2(-g * LOG2E)); }
; static __device__ __forceinline__ void phase_ffn_up(const P& p, int l, char* lds) {
;     ...
; #pragma unroll
;       for (int jj = 0; jj < 4; ++jj) {
;         const int r = (tid >> 3) + 64 * jj, tt = tstart + r;
;         if (r >= 1 && r <= 254 && tt < MEND) {
;           const int pos = tt < MLAT ? (tt & (TLAT - 1)) : ((tt - MLAT) & (TCTX - 1)), slen = tt < MLAT ? TLAT : TCTX;
;           const float fm = pos == 0 ? 0.f : 1.f, fp = pos == slen - 1 ? 0.f : 1.f;
;           const char* rp = tile + r * 528;
;           float o[8];
; #pragma unroll
;           for (int hf = 0; hf < 2; ++hf) {
;             const f32x4 am = *(const f32x4*)(rp - 528 + lca + hf * 16), a0 = *(const f32x4*)(rp + lca + hf * 16), ap = *(const f32x4*)(rp + 528 + lca + hf * 16);
;             const f32x4 gm = *(const f32x4*)(rp - 528 + lcg + hf * 16), g0 = *(const f32x4*)(rp + lcg + hf * 16), gp = *(const f32x4*)(rp + 528 + lcg + hf * 16);
; #pragma unroll
;             for (int e = 0; e < 4; ++e) {
;               const int q = hf * 4 + e;
;               const float ua = wa0[q] * (fm * am[e]) + wa1[q] * a0[e] + wa2[q] * (fp * ap[e]) + ba[q];
;               const float ug = wg0[q] * (fm * gm[e]) + wg1[q] * g0[e] + wg2[q] * (fp * gp[e]) + bg[q];
;               o[q] = silu_f(ug) * ua;
;             }
;           }
;           u32x4 w = {pk2(o[0], o[1]), pk2(o[2], o[3]), pk2(o[4], o[5]), pk2(o[6], o[7])};
;           *(u32x4*)(act + (size_t)tt * DFF + ca0) = w;
;         }
.Lwt_done:
	s_and_saveexec_b64 s[20:21], s[22:23]
	s_cbranch_execz .LBB0_1079
	v_add_u32_e32 v159, v151, v150
	v_cmp_gt_i32_e32 vcc, s39, v158
	s_nop 1
	v_cndmask_b32_e32 v114, v235, v236, vcc
	v_and_b32_e32 v115, v114, v158
	v_cmp_eq_u32_e64 s[100:101], 0, v115
	v_cmp_eq_u32_e32 vcc, v115, v114
	s_nop 3
	s_or_b64 s[100:101], s[100:101], vcc
	s_cbranch_scc0 .Lcf_0
	v_add_u32_e32 v159, v151, v150
	v_cmp_gt_i32_e32 vcc, s39, v158
	ds_read_b128 v[136:139], v159 offset:1904
	ds_read_b128 v[160:163], v159 offset:2432
	v_cndmask_b32_e32 v114, v235, v236, vcc
	v_and_b32_e32 v115, v114, v158
	ds_read_b128 v[164:167], v159 offset:2960
	ds_read_b128 v[168:171], v159 offset:1776
	v_cmp_eq_u32_e32 vcc, 0, v115
	s_waitcnt vmcnt(6) lgkmcnt(2)
	v_pk_mul_f32 v[116:117], v[102:103], v[160:161]
	v_pk_mul_f32 v[162:163], v[104:105], v[162:163]
	v_cndmask_b32_e64 v0, 1.0, 0, vcc
	v_cmp_eq_u32_e32 vcc, v115, v114
	v_pk_mul_f32 v[114:115], v[0:1], v[136:137] op_sel_hi:[0,1]
	v_pk_fma_f32 v[114:115], v[98:99], v[114:115], v[116:117]
	v_cndmask_b32_e64 v134, 1.0, 0, vcc
	s_waitcnt lgkmcnt(1)
	v_pk_mul_f32 v[116:117], v[134:135], v[164:165] op_sel_hi:[0,1]
	s_waitcnt vmcnt(3)
	v_pk_fma_f32 v[114:115], v[106:107], v[116:117], v[114:115]
	v_pk_mul_f32 v[138:139], v[0:1], v[138:139] op_sel_hi:[0,1]
	s_waitcnt vmcnt(1)
	v_pk_add_f32 v[136:137], v[110:111], v[114:115]
	v_pk_fma_f32 v[138:139], v[100:101], v[138:139], v[162:163]
	v_mul_f32_e32 v114, 0xbfb8aa3b, v136
	v_mul_f32_e32 v161, 0xbfb8aa3b, v137
	v_exp_f32_e32 v160, v114
	ds_read_b128 v[114:117], v159 offset:1792
	ds_read_b128 v[172:175], v159 offset:2304
	ds_read_b128 v[176:179], v159 offset:2832
	v_exp_f32_e32 v161, v161
	v_pk_mul_f32 v[162:163], v[134:135], v[166:167] op_sel_hi:[0,1]
	v_pk_fma_f32 v[138:139], v[108:109], v[162:163], v[138:139]
	v_add_f32_e32 v160, 1.0, v160
	v_pk_add_f32 v[138:139], v[112:113], v[138:139]
	s_waitcnt lgkmcnt(3)
	v_pk_mul_f32 v[164:165], v[0:1], v[168:169] op_sel_hi:[0,1]
	s_waitcnt lgkmcnt(1)
	v_pk_mul_f32 v[168:169], v[94:95], v[172:173]
	v_add_f32_e32 v161, 1.0, v161
	v_mul_f32_e32 v162, 0xbfb8aa3b, v138
	v_rcp_f32_e32 v160, v160
	v_pk_fma_f32 v[164:165], v[86:87], v[164:165], v[168:169]
	s_waitcnt lgkmcnt(0)
	v_pk_mul_f32 v[168:169], v[134:135], v[176:177] op_sel_hi:[0,1]
	v_rcp_f32_e32 v161, v161
	v_exp_f32_e32 v166, v162
	v_pk_fma_f32 v[164:165], v[90:91], v[168:169], v[164:165]
	v_pk_mul_f32 v[114:115], v[0:1], v[114:115] op_sel_hi:[0,1]
	v_pk_add_f32 v[162:163], v[82:83], v[164:165]
	v_mul_f32_e32 v164, 0xbfb8aa3b, v139
	v_exp_f32_e32 v164, v164
	v_pk_mul_f32 v[136:137], v[136:137], v[160:161]
	v_add_f32_e32 v160, 1.0, v166
	v_pk_mul_f32 v[136:137], v[162:163], v[136:137]
	v_rcp_f32_e32 v172, v160
	v_pk_mul_f32 v[160:161], v[0:1], v[170:171] op_sel_hi:[0,1]
	v_pk_mul_f32 v[162:163], v[96:97], v[174:175]
	v_pk_mul_f32 v[116:117], v[0:1], v[116:117] op_sel_hi:[0,1]
	v_pk_fma_f32 v[160:161], v[88:89], v[160:161], v[162:163]
	v_pk_mul_f32 v[162:163], v[134:135], v[178:179] op_sel_hi:[0,1]
	v_pk_fma_f32 v[168:169], v[92:93], v[162:163], v[160:161]
	v_add_f32_e32 v160, 1.0, v164
	v_rcp_f32_e32 v173, v160
	ds_read_b128 v[160:163], v159 offset:1920
	ds_read_b128 v[164:167], v159 offset:2448
	v_pk_add_f32 v[174:175], v[84:85], v[168:169]
	ds_read_b128 v[168:171], v159 offset:2976
	v_pk_mul_f32 v[138:139], v[138:139], v[172:173]
	s_waitcnt lgkmcnt(2)
	v_pk_mul_f32 v[160:161], v[0:1], v[160:161] op_sel_hi:[0,1]
	s_waitcnt lgkmcnt(1)
	v_pk_mul_f32 v[164:165], v[70:71], v[164:165]
	v_pk_mul_f32 v[138:139], v[174:175], v[138:139]
	v_pk_fma_f32 v[160:161], v[66:67], v[160:161], v[164:165]
	s_waitcnt lgkmcnt(0)
	v_pk_mul_f32 v[164:165], v[134:135], v[168:169] op_sel_hi:[0,1]
	v_pk_fma_f32 v[160:161], v[74:75], v[164:165], v[160:161]
	ds_read_b128 v[172:175], v159 offset:2320
	ds_read_b128 v[176:179], v159 offset:2848
	s_waitcnt vmcnt(0)
	v_pk_add_f32 v[160:161], v[78:79], v[160:161]
	v_pk_mul_f32 v[162:163], v[0:1], v[162:163] op_sel_hi:[0,1]
	v_mul_f32_e32 v164, 0xbfb8aa3b, v160
	v_exp_f32_e32 v164, v164
	s_waitcnt lgkmcnt(1)
	v_pk_mul_f32 v[168:169], v[58:59], v[172:173]
	v_pk_mul_f32 v[166:167], v[72:73], v[166:167]
	v_pk_fma_f32 v[114:115], v[50:51], v[114:115], v[168:169]
	v_add_f32_e32 v159, 1.0, v164
	v_rcp_f32_e32 v164, v159
	v_mul_f32_e32 v159, 0xbfb8aa3b, v161
	v_exp_f32_e32 v159, v159
	s_waitcnt lgkmcnt(0)
	v_pk_mul_f32 v[168:169], v[134:135], v[176:177] op_sel_hi:[0,1]
	v_pk_fma_f32 v[162:163], v[68:69], v[162:163], v[166:167]
	v_pk_mul_f32 v[166:167], v[134:135], v[170:171] op_sel_hi:[0,1]
	v_add_f32_e32 v159, 1.0, v159
	v_rcp_f32_e32 v165, v159
	v_pk_fma_f32 v[114:115], v[54:55], v[168:169], v[114:115]
	v_pk_fma_f32 v[162:163], v[76:77], v[166:167], v[162:163]
	v_pk_add_f32 v[114:115], v[62:63], v[114:115]
	v_pk_add_f32 v[162:163], v[80:81], v[162:163]
	v_pk_mul_f32 v[160:161], v[160:161], v[164:165]
	v_mul_f32_e32 v159, 0xbfb8aa3b, v162
	v_pk_mul_f32 v[160:161], v[114:115], v[160:161]
	v_mul_f32_e32 v115, 0xbfb8aa3b, v163
	v_exp_f32_e32 v159, v159
	v_exp_f32_e32 v115, v115
	v_pk_mul_f32 v[164:165], v[60:61], v[174:175]
	s_movk_i32 s14, 0x1600
	v_add_f32_e32 v114, 1.0, v159
	v_add_f32_e32 v0, 1.0, v115
	v_rcp_f32_e32 v114, v114
	v_rcp_f32_e32 v115, v0
	v_pk_fma_f32 v[116:117], v[52:53], v[116:117], v[164:165]
	v_pk_mul_f32 v[164:165], v[134:135], v[178:179] op_sel_hi:[0,1]
	v_pk_fma_f32 v[116:117], v[56:57], v[164:165], v[116:117]
	v_pk_mul_f32 v[114:115], v[162:163], v[114:115]
	v_pk_add_f32 v[116:117], v[64:65], v[116:117]
	s_nop 0
	v_pk_mul_f32 v[162:163], v[116:117], v[114:115]
	v_cvt_pk_bf16_f32 v114, v136, v137
	v_cvt_pk_bf16_f32 v115, v138, v139
	v_cvt_pk_bf16_f32 v116, v160, v161
	v_cvt_pk_bf16_f32 v117, v162, v163
	v_mad_i64_i32 v[136:137], s[22:23], v158, s14, v[132:133]
	global_store_dwordx4 v[136:137], v[114:117], off

; #define GLOAD(RA, RB, KT) do { const int kc_ = (KT) * 8 + lc; _Pragma("unroll") for (int j = 0; j < NA; ++j) RA[j] = al.load(j, kc_); _Pragma("unroll") for (int j = 0; j < NB; ++j) RB[j] = bl.load(j, kc_); } while (0)
; #define LWRITE(RA, RB, BUF) do { char* w_ = wa + (BUF) * STAGE; _Pragma("unroll") for (int j = 0; j < NA; ++j) *(u32x4*)(w_ + j * 64 * PITCH) = RA[j]; _Pragma("unroll") for (int j = 0; j < NB; ++j) *(u32x4*)(w_ + AB + j * 64 * PITCH) = RB[j]; } while (0)
; #define GLOAD(RA, RB, KT) do { const int kc_ = (KT) * 8 + lc; _Pragma("unroll") for (int j = 0; j < NA; ++j) RA[j] = al.load(j, kc_); _Pragma("unroll") for (int j = 0; j < NB; ++j) RB[j] = bl.load(j, kc_); } while (0)
; #define LWRITE(RA, RB, BUF) do { char* w_ = wa + (BUF) * STAGE; _Pragma("unroll") for (int j = 0; j < NA; ++j) *(u32x4*)(w_ + j * 64 * RB_) = RA[j]; _Pragma("unroll") for (int j = 0; j < NB; ++j) *(u32x4*)(w_ + AB + j * 64 * RB_) = RB[j]; } while (0)
; #define COMPUTE(BUF, RA, RB, WBUF) do { const char* sb = lds + (BUF) * STAGE; char* w_ = wa + (WBUF) * STAGE; \
;     KSTEP(o0); *(u32x4*)(w_) = RA[0]; *(u32x4*)(w_ + 64 * RB_) = RA[1]; *(u32x4*)(w_ + 128 * RB_) = RA[2]; \
;     KSTEP(o1); *(u32x4*)(w_ + 192 * RB_) = RA[3]; *(u32x4*)(w_ + AB) = RB[0]; *(u32x4*)(w_ + AB + 64 * RB_) = RB[1]; } while (0)
; template <int WM, int WN, int TM, int TN, bool SW = false, class AL, class BL>
; DI void gemm_run(int tid, char* lds, const AL& al, const BL& bl, int nk, f32x16 (&acc)[TM][TN], u32x4 (&ra0)[WM * TM / 2], u32x4 (&rb0)[WN * TN / 2], u32x4 (&ra1)[WM * TM / 2], u32x4 (&rb1)[WN * TN / 2]) {
;     ...
;   const int kl = nk - 1;
;   LWRITE(ra0, rb0, 0);
;   __syncthreads();
; #pragma unroll 1
;   for (int kt = 0; kt < nk; kt += 2) {
;     GLOAD(ra0, rb0, (kt + 2 < kl ? kt + 2 : kl));
;     COMPUTE(0, ra1, rb1, 1);
;     __syncthreads();
;     if (kt + 1 >= nk) break;
;     GLOAD(ra1, rb1, (kt + 3 < kl ? kt + 3 : kl));
;     COMPUTE(1, ra0, rb0, 0);
;     __syncthreads();
;   }
.LBB0_1159:
	ds_read_b128 v[90:93], v183 offset:2304
	v_add_u32_e32 v136, 0, v128
	ds_read_b128 v[94:97], v183 offset:2336
	ds_read_b128 v[98:101], v136 offset:39168
	ds_read_b128 v[102:105], v136 offset:39200
	ds_read_b128 v[106:109], v136 offset:43776
	ds_read_b128 v[110:113], v136 offset:43808
	s_add_i32 s5, s4, 4
	s_min_u32 s5, s5, 43
	v_lshl_or_b32 v0, s5, 7, v120
	s_add_i32 s5, s4, 2
	s_min_u32 s4, s5, 40
	s_waitcnt lgkmcnt(3)
	v_mfma_f32_32x32x16_bf16 v[50:65], v[90:93], v[98:101], v[50:65]
	s_cmp_lt_u32 s5, 42
	s_waitcnt lgkmcnt(1)
	v_mfma_f32_32x32x16_bf16 v[18:33], v[90:93], v[106:109], v[18:33]
	ds_read_b128 v[90:93], v183 offset:6912
	ds_read_b128 v[132:135], v183 offset:6944
	s_waitcnt vmcnt(5)
	ds_write_b128 v178, v[74:77] offset:57600
	s_waitcnt vmcnt(2)
	ds_write_b128 v180, v[86:89]
	ds_read_b128 v[74:77], v183 offset:2368
	ds_read_b128 v[86:89], v136 offset:39232
	v_mfma_f32_32x32x16_bf16 v[50:65], v[94:97], v[102:105], v[50:65]
	s_waitcnt lgkmcnt(6)
	v_mfma_f32_32x32x16_bf16 v[18:33], v[94:97], v[110:113], v[18:33]
	v_lshl_add_u64 v[96:97], v[122:123], 0, v[0:1]
	v_lshl_add_u64 v[94:95], v[116:117], 0, v[0:1]
	s_waitcnt lgkmcnt(5)
	v_mfma_f32_32x32x16_bf16 v[34:49], v[90:93], v[98:101], v[34:49]
	v_lshl_add_u64 v[98:99], v[118:119], 0, v[0:1]
	v_mfma_f32_32x32x16_bf16 v[2:17], v[90:93], v[106:109], v[2:17]
	ds_read_b128 v[90:93], v136 offset:43840
	s_waitcnt lgkmcnt(1)
	v_mfma_f32_32x32x16_bf16 v[50:65], v[74:77], v[86:89], v[50:65]
	s_waitcnt lgkmcnt(0)
	v_mfma_f32_32x32x16_bf16 v[18:33], v[74:77], v[90:93], v[18:33]
	ds_read_b128 v[74:77], v183 offset:6976
	ds_write_b128 v179, v[70:73] offset:64512
	s_waitcnt vmcnt(1)
	ds_write_b128 v129, v[78:81]
	v_mfma_f32_32x32x16_bf16 v[34:49], v[132:135], v[102:105], v[34:49]
	v_mfma_f32_32x32x16_bf16 v[2:17], v[132:135], v[110:113], v[2:17]
	s_waitcnt lgkmcnt(2)
	v_mfma_f32_32x32x16_bf16 v[34:49], v[74:77], v[86:89], v[34:49]
	v_mfma_f32_32x32x16_bf16 v[2:17], v[74:77], v[90:93], v[2:17]
	ds_read_b128 v[70:73], v183 offset:2400
	ds_read_b128 v[74:77], v136 offset:39264
	ds_read_b128 v[78:81], v183 offset:7008
	ds_read_b128 v[86:89], v136 offset:43872
	v_lshl_add_u64 v[90:91], v[114:115], 0, v[0:1]
	ds_write_b128 v181, v[66:69]
	s_waitcnt vmcnt(0)
	ds_write_b128 v182, v[82:85]
	global_load_dwordx4 v[90:93], v[90:91], off
	s_nop 0
	global_load_dwordx4 v[102:105], v[96:97], off
	s_waitcnt lgkmcnt(4)
	v_mfma_f32_32x32x16_bf16 v[50:65], v[70:73], v[74:77], v[50:65]
	s_waitcnt lgkmcnt(2)
	v_mfma_f32_32x32x16_bf16 v[18:33], v[70:73], v[86:89], v[18:33]
	v_lshl_add_u64 v[70:71], v[124:125], 0, v[0:1]
	v_lshl_add_u64 v[72:73], v[126:127], 0, v[0:1]
	global_load_dwordx4 v[94:97], v[94:95], off
	s_nop 0
	global_load_dwordx4 v[98:101], v[98:99], off
	s_nop 0
	global_load_dwordx4 v[106:109], v[70:71], off
	global_load_dwordx4 v[110:113], v[72:73], off
	s_waitcnt lgkmcnt(0)
	s_barrier
	v_lshl_or_b32 v0, s4, 7, v120
	v_mfma_f32_32x32x16_bf16 v[34:49], v[78:81], v[74:77], v[34:49]
	v_lshl_add_u64 v[136:137], v[116:117], 0, v[0:1]
	v_lshl_add_u64 v[138:139], v[124:125], 0, v[0:1]
	v_lshl_add_u64 v[144:145], v[126:127], 0, v[0:1]
	s_mov_b32 s4, s5
	v_mfma_f32_32x32x16_bf16 v[2:17], v[78:81], v[86:89], v[2:17]
	ds_read_b128 v[66:69], v183 offset:57600
	ds_read_b128 v[70:73], v184 offset:57600
	ds_read_b128 v[74:77], v183 offset:57632
	ds_read_b128 v[78:81], v184 offset:57632
	ds_read_b128 v[82:85], v184 offset:62208
	ds_read_b128 v[86:89], v184 offset:62240
	s_waitcnt lgkmcnt(4)
	v_mfma_f32_32x32x16_bf16 v[50:65], v[66:69], v[70:73], v[50:65]
	s_waitcnt lgkmcnt(1)
	v_mfma_f32_32x32x16_bf16 v[18:33], v[66:69], v[82:85], v[18:33]
	ds_read_b128 v[66:69], v183 offset:62208
	ds_read_b128 v[132:135], v183 offset:62240
	s_waitcnt vmcnt(5)
	ds_write_b128 v178, v[90:93] offset:2304
	s_waitcnt vmcnt(4)
	ds_write_b128 v178, v[102:105] offset:29952
	s_waitcnt lgkmcnt(3)
	v_mfma_f32_32x32x16_bf16 v[34:49], v[66:69], v[70:73], v[34:49]
	v_mfma_f32_32x32x16_bf16 v[2:17], v[66:69], v[82:85], v[2:17]
	ds_read_b128 v[66:69], v183 offset:57664
	ds_read_b128 v[70:73], v184 offset:57664
	ds_read_b128 v[82:85], v183 offset:62272
	v_mfma_f32_32x32x16_bf16 v[50:65], v[74:77], v[78:81], v[50:65]
	v_mfma_f32_32x32x16_bf16 v[18:33], v[74:77], v[86:89], v[18:33]
	v_lshl_add_u64 v[74:75], v[114:115], 0, v[0:1]
	s_waitcnt lgkmcnt(5)
	v_mfma_f32_32x32x16_bf16 v[34:49], v[132:135], v[78:81], v[34:49]
	ds_read_b128 v[78:81], v184 offset:62272
	v_mfma_f32_32x32x16_bf16 v[2:17], v[132:135], v[86:89], v[2:17]
	v_lshl_add_u64 v[86:87], v[118:119], 0, v[0:1]
	v_lshl_add_u64 v[88:89], v[122:123], 0, v[0:1]
	s_waitcnt lgkmcnt(2)
	v_mfma_f32_32x32x16_bf16 v[50:65], v[66:69], v[70:73], v[50:65]
	s_waitcnt lgkmcnt(0)
	v_mfma_f32_32x32x16_bf16 v[18:33], v[66:69], v[78:81], v[18:33]
	v_mfma_f32_32x32x16_bf16 v[34:49], v[82:85], v[70:73], v[34:49]
	global_load_dwordx4 v[74:77], v[74:75], off offset:384
	s_nop 0
	global_load_dwordx4 v[70:73], v[136:137], off offset:384
	global_load_dwordx4 v[66:69], v[86:87], off offset:384
	s_waitcnt vmcnt(6)
	ds_write_b128 v178, v[94:97] offset:11520
	s_waitcnt vmcnt(4)
	ds_write_b128 v178, v[106:109] offset:39168
	v_mfma_f32_32x32x16_bf16 v[2:17], v[82:85], v[78:81], v[2:17]
	ds_read_b128 v[82:85], v183 offset:57696
	ds_read_b128 v[132:135], v184 offset:57696
	global_load_dwordx4 v[86:89], v[88:89], off offset:384
	s_nop 0
	global_load_dwordx4 v[78:81], v[138:139], off offset:384
	ds_read_b128 v[136:139], v184 offset:62304
	ds_read_b128 v[140:143], v183 offset:62304
	s_waitcnt lgkmcnt(2)
	v_mfma_f32_32x32x16_bf16 v[50:65], v[82:85], v[132:135], v[50:65]
	s_waitcnt lgkmcnt(1)
	v_mfma_f32_32x32x16_bf16 v[18:33], v[82:85], v[136:139], v[18:33]
	global_load_dwordx4 v[82:85], v[144:145], off offset:384
	ds_write_b128 v178, v[98:101] offset:20736
	s_waitcnt vmcnt(6)
	ds_write_b128 v178, v[110:113] offset:48384
	s_waitcnt lgkmcnt(2)
	v_mfma_f32_32x32x16_bf16 v[34:49], v[140:143], v[132:135], v[34:49]
	v_mfma_f32_32x32x16_bf16 v[2:17], v[140:143], v[136:139], v[2:17]
	s_waitcnt lgkmcnt(0)
	s_barrier
	s_cbranch_scc1 .LBB0_1159
	s_add_i32 s6, s11, 1
	s_cmp_ge_i32 s6, s10
	s_cbranch_scc1 .LBB0_1173
	s_lshl_b32 s4, s11, 5
	v_readlane_b32 s5, v254, 27
	s_add_i32 s21, s5, s4
	s_lshl_b32 s4, s11, 3
	v_readlane_b32 s5, v254, 25
	s_add_i32 s23, s5, s4
	s_mul_i32 s4, s66, s6
	s_add_i32 s7, s94, s4
	s_mov_b32 s24, 0
	s_mov_b32 s25, 0
	s_branch .LBB0_1163
